# P3|P4 barrier: the 64 scan workgroups write back their L2 at their own (early) arrival; the barrier leader no longer writes back (late-tile stores are write-through)
# baseline (speedup 1.0000x reference)
; __device__ __forceinline__ unsigned xb_add(unsigned* p, unsigned v) { return __hip_atomic_fetch_add(p, v, __ATOMIC_RELAXED, __HIP_MEMORY_SCOPE_AGENT); }
; __device__ __forceinline__ void xcd_barrier(const XcdBarrier& b) {
;     asm volatile("s_waitcnt vmcnt(0)" ::: "memory");
;     __syncthreads();
;     if (threadIdx.x == 0) {
;         unsigned* bar = b.bar;
;         __builtin_amdgcn_s_waitcnt(0);
;         unsigned nloc = b.st[0], nx = b.st[1];
;         if (nloc == 0u) { xcd_barrier_complete(bar, b.x, nloc, nx); b.st[0] = nloc; b.st[1] = nx; }
;         const unsigned old = xb_add(&bar[XB_XSUB(b.x)], 1u);
.LBB0_841:
	s_waitcnt vmcnt(0)
	s_barrier
	s_and_saveexec_b64 s[0:1], s[96:97]
	s_cbranch_execz .LBB0_889
	s_cmpk_gt_u32 s2, 63
	s_cbranch_scc1 .Lwb4_skip
	buffer_wbl2 sc1
	s_waitcnt vmcnt(0)
.Lwb4_skip:
	s_add_i32 s3, 0, 0x22960
	v_mov_b32_e32 v1, s3
	s_waitcnt vmcnt(0) expcnt(0) lgkmcnt(0)
	ds_read_b32 v3, v1
	s_add_i32 s3, 0, 0x22964
	v_mov_b32_e32 v1, s3
	ds_read_b32 v1, v1
	s_waitcnt lgkmcnt(1)
	v_cmp_ne_u32_e32 vcc, 0, v3
	s_cbranch_vccnz .LBB0_857
	v_readlane_b32 s6, v240, 0
	v_readlane_b32 s7, v240, 1
	s_load_dwordx2 s[4:5], s[6:7], 0x4
	s_add_u32 s6, s58, 0x1000
	s_addc_u32 s7, s59, 0
	s_add_u32 s8, s58, 0x1100
	s_addc_u32 s9, s59, 0
	s_add_u32 s10, s58, 0x1200
	s_addc_u32 s11, s59, 0
	s_waitcnt lgkmcnt(0)
	s_mul_i32 s3, s4, s34
	s_add_u32 s18, s58, 0x1300
	s_mul_i32 s3, s3, s5
	s_addc_u32 s19, s59, 0
	s_mov_b32 s4, 1
	v_mov_b32_e32 v17, 0
	s_branch .LBB0_845

; __device__ __forceinline__ unsigned xb_ld(unsigned* p)              { return __hip_atomic_load(p, __ATOMIC_RELAXED, __HIP_MEMORY_SCOPE_AGENT); }
; __device__ __forceinline__ unsigned xb_add(unsigned* p, unsigned v) { return __hip_atomic_fetch_add(p, v, __ATOMIC_RELAXED, __HIP_MEMORY_SCOPE_AGENT); }
; #define XB_SPIN(cond, bar) do { unsigned _sp = 0; while (cond) { __builtin_amdgcn_s_sleep(1); \
;     if ((++_sp & 255u) == 0u) { if (xb_ld(&(bar)[XB_TMO])) break; if (_sp > XB_SPIN_CAP) { atomicAdd(&(bar)[XB_TMO], 1u); break; } } } } while (0)
; __device__ __forceinline__ void xcd_barrier(const XcdBarrier& b) {
;     ...
;         unsigned nloc = b.st[0], nx = b.st[1];
;         if (nloc == 0u) { xcd_barrier_complete(bar, b.x, nloc, nx); b.st[0] = nloc; b.st[1] = nx; }
;         const unsigned old = xb_add(&bar[XB_XSUB(b.x)], 1u);
;         asm volatile("buffer_inv sc1" ::: "memory");
;         const unsigned gen = old / nloc;
;         if (old + 1u == (gen + 1u) * nloc) {
;             __builtin_amdgcn_fence(__ATOMIC_RELEASE, "agent");
;             asm volatile("s_waitcnt vmcnt(0)" ::: "memory");
;             const unsigned og = xb_add(&bar[XB_TOP], 1u);
;             const unsigned tg = og / nx;
;             if (og + 1u == (tg + 1u) * nx) xb_add(&bar[XB_TOPGEN], 1u);
;             else XB_SPIN(xb_ld(&bar[XB_TOPGEN]) == tg, bar);
;             asm volatile("" ::: "memory");
;             xb_add(&bar[XB_XGEN(b.x)], 1u);
;             asm volatile("s_waitcnt vmcnt(0)" ::: "memory");
.LBB0_857:
	s_lshl_b32 s3, s90, 8
	s_add_u32 s6, s58, s3
	s_addc_u32 s7, s59, 0
	v_mov_b32_e32 v2, 0x1000
	v_mov_b32_e32 v4, 1
	global_atomic_add v4, v2, v4, s[6:7] offset:1024 sc0
	v_cvt_f32_u32_e32 v2, v3
	v_sub_u32_e32 v5, 0, v3
	buffer_inv sc1
	v_rcp_iflag_f32_e32 v2, v2
	s_nop 0
	v_mul_f32_e32 v2, 0x4f7ffffe, v2
	v_cvt_u32_f32_e32 v2, v2
	v_mul_lo_u32 v5, v5, v2
	v_mul_hi_u32 v5, v2, v5
	v_add_u32_e32 v2, v2, v5
	s_waitcnt vmcnt(0)
	v_mul_hi_u32 v2, v4, v2
	v_mul_lo_u32 v5, v2, v3
	v_sub_u32_e32 v5, v4, v5
	v_add_u32_e32 v6, 1, v2
	v_cmp_ge_u32_e32 vcc, v5, v3
	v_add_u32_e32 v4, 1, v4
	s_nop 0
	v_cndmask_b32_e32 v2, v2, v6, vcc
	v_sub_u32_e32 v6, v5, v3
	v_cndmask_b32_e32 v5, v5, v6, vcc
	v_add_u32_e32 v6, 1, v2
	v_cmp_ge_u32_e32 vcc, v5, v3
	s_nop 1
	v_cndmask_b32_e32 v2, v2, v6, vcc
	v_mul_lo_u32 v5, v3, v2
	v_add_u32_e32 v3, v5, v3
	v_cmp_ne_u32_e32 vcc, v4, v3
	s_waitcnt lgkmcnt(0)
	v_add_u32_e32 v5, 1, v2
	v_mul_lo_u32 v5, v5, v1
	v_mov_b32_e32 v6, 0x3000
	v_mov_b32_e32 v8, 0
	s_cbranch_vccnz .Lxb4_spin
	v_mov_b32_e32 v7, 1
	global_atomic_add v6, v7, s[58:59] offset:1024
